# stacked + attention K tiles loaded one key row per quad (1 cache line per quad) and transposed in-quad with v_cndmask_b32_dpp, both mixers
# baseline (speedup 1.0000x reference)
; __device__ __forceinline__ unsigned cvt_pk_bf16(float lo, float hi) { unsigned r; asm volatile("v_cvt_pk_bf16_f32 %0, %1, %2" : "=v"(r) : "v"(lo), "v"(hi)); return r; }
; __device__ __forceinline__ void attn_tile(const WT& w, float kbound, float mfloor, LAS unsigned char* stg, f32x16 (&O)[2], float& ltot, float& Mq) {
;     ...
;     const int kt0 = max(0, (128 - w.i0) >> 5);
;     bf16x8 ka[4]; u32x4 vv[2][2];
;     ATT_LOAD(kt0, ka, vv);
; #pragma unroll 1
;     for (int kt = kt0; kt < 5; ++kt) {
;         const int j0 = jbase + 32 * kt;
;         bf16x8 nk[4]; u32x4 nv[2][2];
;         { const int ktn = min(kt + 1, 4); ATT_LOAD(ktn, nk, nv); }
;         f32x16 S;
; #pragma unroll
;         for (int i = 0; i < 16; ++i) S[i] = 0.f;
; #pragma unroll
;         for (int c = 0; c < 4; ++c) S = __builtin_amdgcn_mfma_f32_32x32x16_bf16(ka[c], qb[c], S, 0, 0, 0);
;         const int dbase = tq + 128 - 32 * kt - 8 * g;
;         unsigned pw[8];
; #pragma unroll
;         for (int i2 = 0; i2 < 8; ++i2) {
;             float p[2];
; #pragma unroll
;             for (int e = 0; e < 2; ++e) {
;                 const int i = 2 * i2 + e, ko = 16 * (i >> 3) + (i & 7);
;                 const int dist = dbase - ko;
;                 const bool valid = (j0 + 8 * g + ko >= 0) && (dist >= 0) && (dist <= 128);
;                 const float s2 = S[i] - w.slope2 * (float)dist - Mq;
;                 p[e] = valid ? __builtin_amdgcn_exp2f(s2) : 0.f;
;                 lsum += p[e];
;             }
;             pw[i2] = cvt_pk_bf16(p[0], p[1]);
;         }
.LBB0_634:
	s_add_i32 s1, s0, 2
	s_min_u32 s1, s1, 4
	s_lshl_b32 s1, s1, 5
	s_add_i32 s1, s1, s11
	v_and_b32_e32 v206, -4, v155
	v_or_b32_e32 v206, s1, v206
	v_lshlrev_b32_e32 v206, 8, v206
	v_ashrrev_i32_e32 v207, 31, v206
	v_lshl_add_u64 v[206:207], v[140:141], 0, v[206:207]
	v_and_b32_e32 v208, 3, v155
	v_lshlrev_b32_e32 v208, 5, v208
	v_mov_b32_e32 v209, 0
	v_lshl_add_u64 v[206:207], v[206:207], 0, v[208:209]
	v_or_b32_e32 v40, s1, v156
	global_load_dwordx4 v[78:81], v[206:207], off
	global_load_dwordx4 v[82:85], v[206:207], off offset:256
	global_load_dwordx4 v[86:89], v[206:207], off offset:512
	global_load_dwordx4 v[90:93], v[206:207], off offset:768
	v_max_i32_e32 v38, 0, v40
	v_lshlrev_b32_e32 v128, 8, v38
	v_lshl_add_u64 v[38:39], v[138:139], 0, v[128:129]
	global_load_dwordx4 v[74:77], v[38:39], off
	global_load_dwordx4 v[70:73], v[38:39], off offset:16
	v_or_b32_e32 v38, 16, v40
	v_max_i32_e32 v38, 0, v38
	v_lshlrev_b32_e32 v128, 8, v38
	v_lshl_add_u64 v[38:39], v[138:139], 0, v[128:129]
	global_load_dwordx4 v[66:69], v[38:39], off
	global_load_dwordx4 v[94:97], v[38:39], off offset:16
	s_waitcnt vmcnt(8)
	v_mfma_f32_32x32x16_bf16 v[34:49], v[34:37], v[50:53], 0
	v_cmp_lt_i32_e32 vcc, -1, v165
	s_add_i32 s0, s0, 1
	v_mfma_f32_32x32x16_bf16 v[34:49], v[122:125], v[54:57], v[34:49]
	s_waitcnt vmcnt(6)
	v_mfma_f32_32x32x16_bf16 v[34:49], v[118:121], v[58:61], v[34:49]
	s_waitcnt vmcnt(5)
	v_mfma_f32_32x32x16_bf16 v[34:49], v[114:117], v[62:65], v[34:49]
	v_add_u32_e32 v114, 23, v166
	v_cmp_gt_u32_e64 s[4:5], s33, v114
	v_cvt_f32_i32_e32 v114, v114
	v_add_u32_e32 v115, 22, v166
	s_and_b64 vcc, vcc, s[4:5]
	v_cmp_gt_u32_e64 s[4:5], s33, v115
	v_cvt_f32_i32_e32 v115, v115
	s_nop 4
	v_fma_f32 v34, -v163, v114, v34
	v_sub_f32_e32 v34, v34, v164
	v_exp_f32_e32 v34, v34
	v_fma_f32 v35, -v163, v115, v35
	v_sub_f32_e32 v35, v35, v164
	v_exp_f32_e32 v35, v35
	v_cndmask_b32_e32 v34, 0, v34, vcc
	v_cmp_lt_i32_e32 vcc, -2, v165
	s_and_b64 vcc, vcc, s[4:5]
	v_add_f32_e32 v114, v167, v34
	v_cndmask_b32_e32 v35, 0, v35, vcc
	v_add_f32_e32 v114, v35, v114
	v_cvt_pk_bf16_f32 v34, v34, v35
	v_add_u32_e32 v35, 21, v166
	v_cmp_gt_u32_e64 s[4:5], s33, v35
	v_cvt_f32_i32_e32 v35, v35
	v_cmp_lt_i32_e32 vcc, -3, v165
	s_and_b64 vcc, vcc, s[4:5]
	v_fma_f32 v35, -v163, v35, v36
	v_sub_f32_e32 v35, v35, v164
	v_exp_f32_e32 v35, v35
	s_nop 0
	v_cndmask_b32_e32 v35, 0, v35, vcc
	v_add_f32_e32 v36, v35, v114
	v_add_u32_e32 v114, 20, v166
	v_cmp_gt_u32_e64 s[4:5], s33, v114
	v_cvt_f32_i32_e32 v114, v114
	v_cmp_lt_i32_e32 vcc, -4, v165
	s_and_b64 vcc, vcc, s[4:5]
	v_fma_f32 v37, -v163, v114, v37
	v_sub_f32_e32 v37, v37, v164
	v_exp_f32_e32 v37, v37
	s_waitcnt vmcnt(4)
	v_cndmask_b32_e32 v37, 0, v37, vcc
	v_add_f32_e32 v36, v37, v36
	v_cvt_pk_bf16_f32 v35, v35, v37
	v_add_u32_e32 v37, 19, v166
	v_cmp_gt_u32_e64 s[4:5], s33, v37
	v_cvt_f32_i32_e32 v37, v37
	v_cmp_lt_i32_e32 vcc, -5, v165
	s_and_b64 vcc, vcc, s[4:5]
	v_fma_f32 v37, -v163, v37, v38
	v_add_u32_e32 v38, 18, v166
	v_cmp_gt_u32_e64 s[4:5], s33, v38
	v_cvt_f32_i32_e32 v38, v38
	v_sub_f32_e32 v37, v37, v164
	v_exp_f32_e32 v37, v37
	v_fma_f32 v38, -v163, v38, v39
	v_sub_f32_e32 v38, v38, v164
	v_exp_f32_e32 v38, v38
	v_cndmask_b32_e32 v37, 0, v37, vcc
	v_cmp_lt_i32_e32 vcc, -6, v165
	s_and_b64 vcc, vcc, s[4:5]
	v_add_f32_e32 v36, v37, v36
	v_cndmask_b32_e32 v38, 0, v38, vcc
	v_add_f32_e32 v39, v38, v36
	v_cvt_pk_bf16_f32 v36, v37, v38
	v_add_u32_e32 v37, 17, v166
	v_cmp_gt_u32_e64 s[4:5], s33, v37
	v_cvt_f32_i32_e32 v37, v37
	v_cmp_lt_i32_e32 vcc, -7, v165
	s_and_b64 vcc, vcc, s[4:5]
	v_fma_f32 v37, -v163, v37, v40
	v_sub_f32_e32 v37, v37, v164
	v_exp_f32_e32 v37, v37
	v_add_u32_e32 v40, 6, v166
	v_cndmask_b32_e32 v37, 0, v37, vcc
	v_add_f32_e32 v38, v37, v39
	v_add_u32_e32 v39, 16, v166
	v_cmp_gt_u32_e64 s[4:5], s33, v39
	v_cvt_f32_i32_e32 v39, v39
	v_cmp_lt_i32_e32 vcc, -8, v165
	s_and_b64 vcc, vcc, s[4:5]
	v_fma_f32 v39, -v163, v39, v41
	v_sub_f32_e32 v39, v39, v164
	v_exp_f32_e32 v39, v39
	s_nop 0
	v_cndmask_b32_e32 v39, 0, v39, vcc
	v_add_f32_e32 v38, v39, v38
	v_cvt_pk_bf16_f32 v37, v37, v39
	v_add_u32_e32 v39, 7, v166
	v_cmp_gt_u32_e64 s[4:5], s33, v39
	v_cvt_f32_i32_e32 v39, v39
	v_cmp_lt_i32_e32 vcc, s34, v165
	s_and_b64 vcc, vcc, s[4:5]
	v_cmp_gt_u32_e64 s[4:5], s33, v40
	v_cvt_f32_i32_e32 v40, v40
	v_fma_f32 v39, -v163, v39, v42
	v_sub_f32_e32 v39, v39, v164
	v_exp_f32_e32 v39, v39
	v_fma_f32 v40, -v163, v40, v43
	v_sub_f32_e32 v40, v40, v164
	v_exp_f32_e32 v40, v40
	v_cndmask_b32_e32 v39, 0, v39, vcc
	v_cmp_lt_i32_e32 vcc, s35, v165
	s_and_b64 vcc, vcc, s[4:5]
	v_add_f32_e32 v38, v39, v38
	v_cndmask_b32_e32 v40, 0, v40, vcc
	v_add_f32_e32 v41, v40, v38
	v_cvt_pk_bf16_f32 v38, v39, v40
	v_add_u32_e32 v39, 5, v166
	v_cmp_gt_u32_e64 s[4:5], s33, v39
	v_cvt_f32_i32_e32 v39, v39
	v_cmp_lt_i32_e32 vcc, s48, v165
	s_and_b64 vcc, vcc, s[4:5]
	v_add_u32_e32 v42, 2, v166
	v_fma_f32 v39, -v163, v39, v44
	v_sub_f32_e32 v39, v39, v164
	v_exp_f32_e32 v39, v39
	s_nop 0
	v_cndmask_b32_e32 v39, 0, v39, vcc
	v_add_f32_e32 v40, v39, v41
	v_add_u32_e32 v41, 4, v166
	v_cmp_gt_u32_e64 s[4:5], s33, v41
	v_cvt_f32_i32_e32 v41, v41
	v_cmp_lt_i32_e32 vcc, s49, v165
	s_and_b64 vcc, vcc, s[4:5]
	v_fma_f32 v41, -v163, v41, v45
	v_sub_f32_e32 v41, v41, v164
	v_exp_f32_e32 v41, v41
	s_nop 0
	v_cndmask_b32_e32 v41, 0, v41, vcc
	v_add_f32_e32 v40, v41, v40
	v_cvt_pk_bf16_f32 v39, v39, v41
	v_add_u32_e32 v41, 3, v166
	v_cmp_gt_u32_e64 s[4:5], s33, v41
	v_cvt_f32_i32_e32 v41, v41
	v_cmp_lt_i32_e32 vcc, s50, v165
	s_and_b64 vcc, vcc, s[4:5]
	v_cmp_gt_u32_e64 s[4:5], s33, v42
	v_cvt_f32_i32_e32 v42, v42
	v_fma_f32 v41, -v163, v41, v46
	v_sub_f32_e32 v41, v41, v164
	v_exp_f32_e32 v41, v41
	v_fma_f32 v42, -v163, v42, v47
	v_sub_f32_e32 v42, v42, v164
	v_exp_f32_e32 v42, v42
	v_cndmask_b32_e32 v41, 0, v41, vcc
	v_cmp_lt_i32_e32 vcc, s51, v165
	s_and_b64 vcc, vcc, s[4:5]
	v_add_f32_e32 v40, v41, v40
	v_cndmask_b32_e32 v42, 0, v42, vcc
	v_add_f32_e32 v46, v42, v40
	v_cvt_pk_bf16_f32 v40, v41, v42
	v_add_u32_e32 v41, 1, v166
	v_cmp_gt_u32_e64 s[4:5], s33, v41
	v_cvt_f32_i32_e32 v41, v41
	v_cmp_lt_i32_e32 vcc, s52, v165
	s_and_b64 vcc, vcc, s[4:5]
	v_cmp_gt_u32_e64 s[4:5], s33, v166
	v_fma_f32 v41, -v163, v41, v48
	v_sub_f32_e32 v41, v41, v164
	v_exp_f32_e32 v41, v41
	s_nop 0
	v_cndmask_b32_e32 v47, 0, v41, vcc
	v_cvt_f32_i32_e32 v41, v166
	v_cmp_lt_i32_e32 vcc, s53, v165
	s_and_b64 vcc, vcc, s[4:5]
	v_add_u32_e32 v165, 32, v165
	v_fma_f32 v41, -v163, v41, v49
	v_sub_f32_e32 v41, v41, v164
	v_exp_f32_e32 v41, v41
	v_subrev_u32_e32 v166, 32, v166
	s_cmp_lt_u32 s0, 4
	v_cndmask_b32_e32 v48, 0, v41, vcc
	v_cvt_pk_bf16_f32 v41, v47, v48
	ds_write_b128 v160, v[102:105]
	ds_write_b128 v160, v[106:109] offset:16
	ds_read_b64_tr_b16 v[42:43], v161
	ds_read_b64_tr_b16 v[44:45], v161 offset:256
	s_waitcnt lgkmcnt(0)
; __device__ __forceinline__ unsigned cvt_pk_bf16(float lo, float hi) { unsigned r; asm volatile("v_cvt_pk_bf16_f32 %0, %1, %2" : "=v"(r) : "v"(lo), "v"(hi)); return r; }
; #define LAS __attribute__((address_space(3)))
; __device__ __forceinline__ void attn_tile(const WT& w, float kbound, float mfloor, LAS unsigned char* stg, f32x16 (&O)[2], float& ltot, float& Mq) {
;     ...
; #pragma unroll
;         for (int t = 0; t < 2; ++t) {
;             LAS unsigned char* wp = stg + (lane & 2) * 512 + (lane >> 2) * 64 + (lane & 1) * 32;
;             *(LAS u32x4*)wp = vv[t][0]; *(LAS u32x4*)(wp + 16) = vv[t][1];
;             asm volatile("" ::: "memory");
; #pragma unroll
;             for (int dt = 0; dt < 2; ++dt) {
;                 const LAS unsigned char* rp = stg + dt * 1024 + (8 * g + ((lane & 15) >> 2)) * 64 + (16 * ((lane >> 4) & 1) + 4 * (lane & 3)) * 2;
;                 const s16x4 lo4 = __builtin_amdgcn_ds_read_tr16_b64_v4i16((LAS s16x4*)rp), hi4 = __builtin_amdgcn_ds_read_tr16_b64_v4i16((LAS s16x4*)(rp + 256));
;                 const bf16x8 va = {lo4[0], lo4[1], lo4[2], lo4[3], hi4[0], hi4[1], hi4[2], hi4[3]};
;                 O[dt] = __builtin_amdgcn_mfma_f32_32x32x16_bf16(va, pb[t], O[dt], 0, 0, 0);
;             }
;             asm volatile("" ::: "memory");
;         }
; #pragma unroll
;         for (int c = 0; c < 4; ++c) ka[c] = nk[c];
;         vv[0][0] = nv[0][0]; vv[0][1] = nv[0][1]; vv[1][0] = nv[1][0]; vv[1][1] = nv[1][1];
; __device__ __forceinline__ void p2_attention(const Args& a, LAS unsigned char* lds) {
;     ...
;             attn_tile(w, kbB, sink2, stg, O, l, Mq);
;             l += __builtin_amdgcn_exp2f(sink2 - Mq);
;             const float inv = 1.0f / l;
;             bf16_t* dst = CAT + (size_t)(b * SEQ + i0 + tq) * DM + 512 + hq * 64;
; #pragma unroll
;             for (int dt = 0; dt < 2; ++dt)
; #pragma unroll
;                 for (int i4 = 0; i4 < 4; ++i4) {
;                     u32x2 pkw; pkw.x = cvt_pk_bf16(O[dt][4 * i4] * inv, O[dt][4 * i4 + 1] * inv); pkw.y = cvt_pk_bf16(O[dt][4 * i4 + 2] * inv, O[dt][4 * i4 + 3] * inv);
;                     *(u32x2*)(dst + 32 * dt + 8 * i4 + 4 * g) = pkw;
;                 }
	v_mfma_f32_32x32x16_bf16 v[18:33], v[42:45], v[34:37], v[18:33]
	ds_read_b64_tr_b16 v[42:43], v161 offset:1024
	ds_read_b64_tr_b16 v[44:45], v161 offset:1280
	ds_write_b128 v160, v[110:113]
	ds_write_b128 v160, v[98:101] offset:16
	s_waitcnt vmcnt(0)
	v_mov_b64_e32 v[100:101], v[96:97]
	v_mov_b64_e32 v[98:99], v[94:95]
	v_mov_b32_e32 v102, v74
	s_waitcnt lgkmcnt(2)
	v_mfma_f32_32x32x16_bf16 v[2:17], v[42:45], v[34:37], v[2:17]
	ds_read_b64_tr_b16 v[34:35], v161
	ds_read_b64_tr_b16 v[36:37], v161 offset:256
	v_mov_b32_e32 v103, v75
	v_mov_b32_e32 v104, v76
	v_mov_b32_e32 v105, v77
	v_mov_b32_e32 v106, v70
	v_mov_b32_e32 v107, v71
	v_mov_b32_e32 v108, v72
	s_waitcnt lgkmcnt(0)
	v_mfma_f32_32x32x16_bf16 v[18:33], v[34:37], v[38:41], v[18:33]
	ds_read_b64_tr_b16 v[34:35], v161 offset:1024
	ds_read_b64_tr_b16 v[36:37], v161 offset:1280
	v_mov_b32_e32 v109, v73
	v_mov_b32_e32 v110, v66
	v_mov_b32_e32 v111, v67
	v_mov_b32_e32 v112, v68
	v_mov_b32_e32 v113, v69
	s_waitcnt lgkmcnt(0)
	v_mfma_f32_32x32x16_bf16 v[2:17], v[34:37], v[38:41], v[2:17]
	v_add_f32_e32 v34, v47, v46
	v_add_f32_e32 v167, v48, v34
	s_mov_b32 vcc_lo, 0xaaaaaaaa
	s_mov_b32 vcc_hi, 0xaaaaaaaa
	v_cndmask_b32_dpp v188, v78, v82, vcc quad_perm:[1,0,3,2] row_mask:0xf bank_mask:0xf
	v_cndmask_b32_dpp v189, v79, v83, vcc quad_perm:[1,0,3,2] row_mask:0xf bank_mask:0xf
	v_cndmask_b32_dpp v190, v80, v84, vcc quad_perm:[1,0,3,2] row_mask:0xf bank_mask:0xf
	v_cndmask_b32_dpp v191, v81, v85, vcc quad_perm:[1,0,3,2] row_mask:0xf bank_mask:0xf
	v_cndmask_b32_dpp v196, v86, v90, vcc quad_perm:[1,0,3,2] row_mask:0xf bank_mask:0xf
	v_cndmask_b32_dpp v197, v87, v91, vcc quad_perm:[1,0,3,2] row_mask:0xf bank_mask:0xf
	v_cndmask_b32_dpp v198, v88, v92, vcc quad_perm:[1,0,3,2] row_mask:0xf bank_mask:0xf
	v_cndmask_b32_dpp v199, v89, v93, vcc quad_perm:[1,0,3,2] row_mask:0xf bank_mask:0xf
	s_mov_b32 vcc_lo, 0x55555555
	s_mov_b32 vcc_hi, 0x55555555
	v_cndmask_b32_dpp v184, v82, v78, vcc quad_perm:[1,0,3,2] row_mask:0xf bank_mask:0xf
	v_cndmask_b32_dpp v185, v83, v79, vcc quad_perm:[1,0,3,2] row_mask:0xf bank_mask:0xf
	v_cndmask_b32_dpp v186, v84, v80, vcc quad_perm:[1,0,3,2] row_mask:0xf bank_mask:0xf
	v_cndmask_b32_dpp v187, v85, v81, vcc quad_perm:[1,0,3,2] row_mask:0xf bank_mask:0xf
	v_cndmask_b32_dpp v192, v90, v86, vcc quad_perm:[1,0,3,2] row_mask:0xf bank_mask:0xf
	v_cndmask_b32_dpp v193, v91, v87, vcc quad_perm:[1,0,3,2] row_mask:0xf bank_mask:0xf
	v_cndmask_b32_dpp v194, v92, v88, vcc quad_perm:[1,0,3,2] row_mask:0xf bank_mask:0xf
	v_cndmask_b32_dpp v195, v93, v89, vcc quad_perm:[1,0,3,2] row_mask:0xf bank_mask:0xf
	s_mov_b32 vcc_lo, 0xcccccccc
	s_mov_b32 vcc_hi, 0xcccccccc
	s_nop 1
	v_cndmask_b32_dpp v118, v184, v192, vcc quad_perm:[2,3,0,1] row_mask:0xf bank_mask:0xf
	v_cndmask_b32_dpp v119, v185, v193, vcc quad_perm:[2,3,0,1] row_mask:0xf bank_mask:0xf
	v_cndmask_b32_dpp v120, v186, v194, vcc quad_perm:[2,3,0,1] row_mask:0xf bank_mask:0xf
	v_cndmask_b32_dpp v121, v187, v195, vcc quad_perm:[2,3,0,1] row_mask:0xf bank_mask:0xf
	v_cndmask_b32_dpp v114, v188, v196, vcc quad_perm:[2,3,0,1] row_mask:0xf bank_mask:0xf
	v_cndmask_b32_dpp v115, v189, v197, vcc quad_perm:[2,3,0,1] row_mask:0xf bank_mask:0xf
	v_cndmask_b32_dpp v116, v190, v198, vcc quad_perm:[2,3,0,1] row_mask:0xf bank_mask:0xf
	v_cndmask_b32_dpp v117, v191, v199, vcc quad_perm:[2,3,0,1] row_mask:0xf bank_mask:0xf
	s_mov_b32 vcc_lo, 0x33333333
	s_mov_b32 vcc_hi, 0x33333333
	v_cndmask_b32_dpp v34, v192, v184, vcc quad_perm:[2,3,0,1] row_mask:0xf bank_mask:0xf
	v_cndmask_b32_dpp v35, v193, v185, vcc quad_perm:[2,3,0,1] row_mask:0xf bank_mask:0xf
	v_cndmask_b32_dpp v36, v194, v186, vcc quad_perm:[2,3,0,1] row_mask:0xf bank_mask:0xf
	v_cndmask_b32_dpp v37, v195, v187, vcc quad_perm:[2,3,0,1] row_mask:0xf bank_mask:0xf
	v_cndmask_b32_dpp v122, v196, v188, vcc quad_perm:[2,3,0,1] row_mask:0xf bank_mask:0xf
	v_cndmask_b32_dpp v123, v197, v189, vcc quad_perm:[2,3,0,1] row_mask:0xf bank_mask:0xf
	v_cndmask_b32_dpp v124, v198, v190, vcc quad_perm:[2,3,0,1] row_mask:0xf bank_mask:0xf
	v_cndmask_b32_dpp v125, v199, v191, vcc quad_perm:[2,3,0,1] row_mask:0xf bank_mask:0xf
	s_cbranch_scc1 .LBB0_634
	ds_bpermute_b32 v34, v127, v167
	v_sub_f32_e32 v35, v137, v164
	v_exp_f32_e32 v35, v35
	s_lshl_b32 s8, s8, 1
	v_mov_b32_e32 v137, v129
	s_waitcnt lgkmcnt(0)
	v_add_f32_e32 v34, v167, v34
	v_add_f32_e32 v35, v35, v34
	v_div_scale_f32 v36, s[0:1], v35, v35, 1.0
	v_rcp_f32_e32 v37, v36
	v_div_scale_f32 v38, vcc, 1.0, v35, 1.0
	v_or_b32_e32 v34, s10, v151
	v_fma_f32 v39, -v36, v37, 1.0
	v_fmac_f32_e32 v37, v39, v37
	v_mul_f32_e32 v39, v38, v37
	v_fma_f32 v40, -v36, v39, v38
	v_fmac_f32_e32 v39, v40, v37
	v_fma_f32 v36, -v36, v39, v38
	v_div_fmas_f32 v36, v36, v37, v39
	v_div_fixup_f32 v36, v36, v35, 1.0
	v_ashrrev_i32_e32 v35, 31, v34
	v_lshlrev_b64 v[34:35], 11, v[34:35]
	v_lshl_add_u64 v[34:35], s[6:7], 0, v[34:35]
	v_mul_f32_e32 v18, v18, v36
	v_mul_f32_e32 v19, v19, v36
	v_lshl_add_u64 v[34:35], v[34:35], 0, s[8:9]
	v_cvt_pk_bf16_f32 v18, v18, v19
	v_mul_f32_e32 v19, v20, v36
	v_lshl_add_u64 v[34:35], v[34:35], 0, v[136:137]
	v_mul_f32_e32 v20, v21, v36
	v_cvt_pk_bf16_f32 v19, v19, v20
	global_store_dwordx2 v[34:35], v[18:19], off offset:1024
	v_mul_f32_e32 v18, v22, v36
	v_mul_f32_e32 v19, v23, v36
	v_cvt_pk_bf16_f32 v18, v18, v19
	v_mul_f32_e32 v19, v24, v36
	v_mul_f32_e32 v20, v25, v36
	v_cvt_pk_bf16_f32 v19, v19, v20
	global_store_dwordx2 v[34:35], v[18:19], off offset:1040
	v_mul_f32_e32 v18, v26, v36
	v_mul_f32_e32 v19, v27, v36
	v_cvt_pk_bf16_f32 v18, v18, v19
	v_mul_f32_e32 v19, v28, v36
	v_mul_f32_e32 v20, v29, v36
	v_cvt_pk_bf16_f32 v19, v19, v20
	global_store_dwordx2 v[34:35], v[18:19], off offset:1056
	v_mul_f32_e32 v18, v30, v36
	v_mul_f32_e32 v19, v31, v36
	v_cvt_pk_bf16_f32 v18, v18, v19
	v_mul_f32_e32 v19, v32, v36
	v_mul_f32_e32 v2, v2, v36
	v_mul_f32_e32 v3, v3, v36
	v_mul_f32_e32 v20, v33, v36
	v_cvt_pk_bf16_f32 v19, v19, v20
	global_store_dwordx2 v[34:35], v[18:19], off offset:1072
	v_cvt_pk_bf16_f32 v2, v2, v3
	v_mul_f32_e32 v3, v4, v36
	v_mul_f32_e32 v4, v5, v36
	v_cvt_pk_bf16_f32 v3, v3, v4
	global_store_dwordx2 v[34:35], v[2:3], off offset:1088
	v_mul_f32_e32 v2, v6, v36
	v_mul_f32_e32 v3, v7, v36
	v_cvt_pk_bf16_f32 v2, v2, v3
	v_mul_f32_e32 v3, v8, v36
	v_mul_f32_e32 v4, v9, v36
	v_cvt_pk_bf16_f32 v3, v3, v4
	global_store_dwordx2 v[34:35], v[2:3], off offset:1104
	v_mul_f32_e32 v2, v10, v36
	v_mul_f32_e32 v3, v11, v36
	v_cvt_pk_bf16_f32 v2, v2, v3
	v_mul_f32_e32 v3, v12, v36
	v_mul_f32_e32 v4, v13, v36
	v_cvt_pk_bf16_f32 v3, v3, v4
	global_store_dwordx2 v[34:35], v[2:3], off offset:1120
	v_mul_f32_e32 v2, v14, v36
	v_mul_f32_e32 v3, v15, v36
	s_add_i32 s14, s14, s23
	s_add_i32 s28, s28, s29
	v_cvt_pk_bf16_f32 v2, v2, v3
	v_mul_f32_e32 v3, v16, v36
	s_cmpk_gt_i32 s14, 0xfff
	v_mul_f32_e32 v4, v17, v36
	v_cvt_pk_bf16_f32 v3, v3, v4
	global_store_dwordx2 v[34:35], v[2:3], off offset:1136
	s_cbranch_scc0 .LBB0_633

; __device__ __forceinline__ unsigned cvt_pk_bf16(float lo, float hi) { unsigned r; asm volatile("v_cvt_pk_bf16_f32 %0, %1, %2" : "=v"(r) : "v"(lo), "v"(hi)); return r; }
; #define LAS __attribute__((address_space(3)))
; __device__ __forceinline__ void attn_tile(const WT& w, float kbound, float mfloor, LAS unsigned char* stg, f32x16 (&O)[2], float& ltot, float& Mq) {
;     ...
;     const int kt0 = max(0, (128 - w.i0) >> 5);
;     bf16x8 ka[4]; u32x4 vv[2][2];
;     ATT_LOAD(kt0, ka, vv);
; #pragma unroll 1
;     for (int kt = kt0; kt < 5; ++kt) {
;         const int j0 = jbase + 32 * kt;
;         bf16x8 nk[4]; u32x4 nv[2][2];
;         { const int ktn = min(kt + 1, 4); ATT_LOAD(ktn, nk, nv); }
;         f32x16 S;
; #pragma unroll
;         for (int i = 0; i < 16; ++i) S[i] = 0.f;
; #pragma unroll
;         for (int c = 0; c < 4; ++c) S = __builtin_amdgcn_mfma_f32_32x32x16_bf16(ka[c], qb[c], S, 0, 0, 0);
;         const int dbase = tq + 128 - 32 * kt - 8 * g;
;         unsigned pw[8];
; #pragma unroll
;         for (int i2 = 0; i2 < 8; ++i2) {
;             float p[2];
; #pragma unroll
;             for (int e = 0; e < 2; ++e) {
;                 const int i = 2 * i2 + e, ko = 16 * (i >> 3) + (i & 7);
;                 const int dist = dbase - ko;
;                 const bool valid = (j0 + 8 * g + ko >= 0) && (dist >= 0) && (dist <= 128);
;                 const float s2 = S[i] - w.slope2 * (float)dist - Mq;
;                 p[e] = valid ? __builtin_amdgcn_exp2f(s2) : 0.f;
;                 lsum += p[e];
;             }
;             pw[i2] = cvt_pk_bf16(p[0], p[1]);
;         }
;         bf16x8 pb[2];
;         { u32x4 t0 = {pw[0], pw[1], pw[2], pw[3]}, t1 = {pw[4], pw[5], pw[6], pw[7]}; pb[0] = __builtin_bit_cast(bf16x8, t0); pb[1] = __builtin_bit_cast(bf16x8, t1); }
; #pragma unroll
;         for (int t = 0; t < 2; ++t) {
;             LAS unsigned char* wp = stg + (lane & 2) * 512 + (lane >> 2) * 64 + (lane & 1) * 32;
;             *(LAS u32x4*)wp = vv[t][0]; *(LAS u32x4*)(wp + 16) = vv[t][1];
.LBB0_652:
	s_add_i32 s0, s80, 2
	s_min_u32 s0, s0, 4
	s_lshl_b32 s0, s0, 5
	s_add_i32 s0, s0, s1
	v_and_b32_e32 v206, -4, v153
	v_add_u32_e32 v206, s0, v206
	v_ashrrev_i32_e32 v207, 31, v206
	v_lshlrev_b64 v[206:207], s77, v[206:207]
	v_add_u32_e32 v40, s0, v154
	v_lshl_add_u64 v[206:207], v[206:207], 1, v[148:149]
	v_and_b32_e32 v208, 3, v153
	v_lshlrev_b32_e32 v208, 5, v208
	v_mov_b32_e32 v209, 0
	v_lshl_add_u64 v[206:207], v[206:207], 0, v[208:209]
	s_lshl_b32 s8, 2, s77
	s_mov_b32 s9, 0
	v_lshl_add_u64 v[210:211], v[206:207], 0, s[8:9]
	v_lshl_add_u64 v[212:213], v[210:211], 0, s[8:9]
	v_lshl_add_u64 v[214:215], v[212:213], 0, s[8:9]
	v_max_i32_e32 v128, 0, v40
	global_load_dwordx4 v[78:81], v[206:207], off
	global_load_dwordx4 v[82:85], v[210:211], off
	global_load_dwordx4 v[86:89], v[212:213], off
	global_load_dwordx4 v[90:93], v[214:215], off
	v_lshlrev_b64 v[38:39], s77, v[128:129]
	v_lshl_add_u64 v[38:39], v[38:39], 1, v[146:147]
	global_load_dwordx4 v[74:77], v[38:39], off
	global_load_dwordx4 v[70:73], v[38:39], off offset:16
	v_add_u32_e32 v38, 16, v40
	v_max_i32_e32 v128, 0, v38
	v_lshlrev_b64 v[38:39], s77, v[128:129]
	v_lshl_add_u64 v[38:39], v[38:39], 1, v[146:147]
	global_load_dwordx4 v[66:69], v[38:39], off
	global_load_dwordx4 v[94:97], v[38:39], off offset:16
	s_waitcnt vmcnt(8)
	v_mfma_f32_32x32x16_bf16 v[34:49], v[34:37], v[50:53], 0
	v_cmp_lt_i32_e32 vcc, -1, v137
	s_add_i32 s80, s80, 1
	v_mfma_f32_32x32x16_bf16 v[34:49], v[122:125], v[54:57], v[34:49]
	s_waitcnt vmcnt(6)
	v_mfma_f32_32x32x16_bf16 v[34:49], v[118:121], v[58:61], v[34:49]
	s_waitcnt vmcnt(5)
	v_mfma_f32_32x32x16_bf16 v[34:49], v[114:117], v[62:65], v[34:49]
	v_add_u32_e32 v114, 23, v165
	v_cmp_gt_u32_e64 s[8:9], s23, v114
	v_cvt_f32_i32_e32 v114, v114
	v_add_u32_e32 v115, 22, v165
	s_and_b64 vcc, vcc, s[8:9]
	v_cmp_gt_u32_e64 s[8:9], s23, v115
	v_cvt_f32_i32_e32 v115, v115
	s_nop 4
	v_fma_f32 v34, -v163, v114, v34
	v_sub_f32_e32 v34, v34, v164
	v_exp_f32_e32 v34, v34
	v_fma_f32 v35, -v163, v115, v35
	v_sub_f32_e32 v35, v35, v164
	v_exp_f32_e32 v35, v35
	v_cndmask_b32_e32 v34, 0, v34, vcc
	v_cmp_lt_i32_e32 vcc, -2, v137
	s_and_b64 vcc, vcc, s[8:9]
	v_add_f32_e32 v114, v166, v34
	v_cndmask_b32_e32 v35, 0, v35, vcc
	v_add_f32_e32 v114, v35, v114
	v_cvt_pk_bf16_f32 v34, v34, v35
	v_add_u32_e32 v35, 21, v165
	v_cmp_gt_u32_e64 s[8:9], s23, v35
	v_cvt_f32_i32_e32 v35, v35
	v_cmp_lt_i32_e32 vcc, -3, v137
	s_and_b64 vcc, vcc, s[8:9]
	v_fma_f32 v35, -v163, v35, v36
	v_sub_f32_e32 v35, v35, v164
	v_exp_f32_e32 v35, v35
	s_nop 0
	v_cndmask_b32_e32 v35, 0, v35, vcc
	v_add_f32_e32 v36, v35, v114
	v_add_u32_e32 v114, 20, v165
	v_cmp_gt_u32_e64 s[8:9], s23, v114
	v_cvt_f32_i32_e32 v114, v114
	v_cmp_lt_i32_e32 vcc, -4, v137
	s_and_b64 vcc, vcc, s[8:9]
	v_fma_f32 v37, -v163, v114, v37
	v_sub_f32_e32 v37, v37, v164
	v_exp_f32_e32 v37, v37
	s_waitcnt vmcnt(4)
	v_cndmask_b32_e32 v37, 0, v37, vcc
	v_add_f32_e32 v36, v37, v36
	v_cvt_pk_bf16_f32 v35, v35, v37
	v_add_u32_e32 v37, 19, v165
	v_cmp_gt_u32_e64 s[8:9], s23, v37
	v_cvt_f32_i32_e32 v37, v37
	v_cmp_lt_i32_e32 vcc, -5, v137
	s_and_b64 vcc, vcc, s[8:9]
	v_fma_f32 v37, -v163, v37, v38
	v_add_u32_e32 v38, 18, v165
	v_cmp_gt_u32_e64 s[8:9], s23, v38
	v_cvt_f32_i32_e32 v38, v38
	v_sub_f32_e32 v37, v37, v164
	v_exp_f32_e32 v37, v37
	v_fma_f32 v38, -v163, v38, v39
	v_sub_f32_e32 v38, v38, v164
	v_exp_f32_e32 v38, v38
	v_cndmask_b32_e32 v37, 0, v37, vcc
	v_cmp_lt_i32_e32 vcc, -6, v137
	s_and_b64 vcc, vcc, s[8:9]
	v_add_f32_e32 v36, v37, v36
	v_cndmask_b32_e32 v38, 0, v38, vcc
	v_add_f32_e32 v39, v38, v36
	v_cvt_pk_bf16_f32 v36, v37, v38
	v_add_u32_e32 v37, 17, v165
	v_cmp_gt_u32_e64 s[8:9], s23, v37
	v_cvt_f32_i32_e32 v37, v37
	v_cmp_lt_i32_e32 vcc, -7, v137
	s_and_b64 vcc, vcc, s[8:9]
	v_fma_f32 v37, -v163, v37, v40
	v_sub_f32_e32 v37, v37, v164
	v_exp_f32_e32 v37, v37
	v_add_u32_e32 v40, 6, v165
	v_cndmask_b32_e32 v37, 0, v37, vcc
	v_add_f32_e32 v38, v37, v39
	v_add_u32_e32 v39, 16, v165
	v_cmp_gt_u32_e64 s[8:9], s23, v39
	v_cvt_f32_i32_e32 v39, v39
	v_cmp_lt_i32_e32 vcc, -8, v137
	s_and_b64 vcc, vcc, s[8:9]
	v_fma_f32 v39, -v163, v39, v41
	v_sub_f32_e32 v39, v39, v164
	v_exp_f32_e32 v39, v39
	s_nop 0
	v_cndmask_b32_e32 v39, 0, v39, vcc
	v_add_f32_e32 v38, v39, v38
	v_cvt_pk_bf16_f32 v37, v37, v39
	v_add_u32_e32 v39, 7, v165
	v_cmp_gt_u32_e64 s[8:9], s23, v39
	v_cvt_f32_i32_e32 v39, v39
	v_cmp_lt_i32_e32 vcc, s33, v137
	s_and_b64 vcc, vcc, s[8:9]
	v_cmp_gt_u32_e64 s[8:9], s23, v40
	v_cvt_f32_i32_e32 v40, v40
	v_fma_f32 v39, -v163, v39, v42
	v_sub_f32_e32 v39, v39, v164
	v_exp_f32_e32 v39, v39
	v_fma_f32 v40, -v163, v40, v43
	v_sub_f32_e32 v40, v40, v164
	v_exp_f32_e32 v40, v40
	v_cndmask_b32_e32 v39, 0, v39, vcc
	v_cmp_lt_i32_e32 vcc, s48, v137
	s_and_b64 vcc, vcc, s[8:9]
	v_add_f32_e32 v38, v39, v38
	v_cndmask_b32_e32 v40, 0, v40, vcc
	v_add_f32_e32 v41, v40, v38
	v_cvt_pk_bf16_f32 v38, v39, v40
	v_add_u32_e32 v39, 5, v165
	v_cmp_gt_u32_e64 s[8:9], s23, v39
	v_cvt_f32_i32_e32 v39, v39
	v_cmp_lt_i32_e32 vcc, s49, v137
	s_and_b64 vcc, vcc, s[8:9]
	v_add_u32_e32 v42, 2, v165
	v_fma_f32 v39, -v163, v39, v44
	v_sub_f32_e32 v39, v39, v164
	v_exp_f32_e32 v39, v39
	s_nop 0
	v_cndmask_b32_e32 v39, 0, v39, vcc
	v_add_f32_e32 v40, v39, v41
	v_add_u32_e32 v41, 4, v165
	v_cmp_gt_u32_e64 s[8:9], s23, v41
	v_cvt_f32_i32_e32 v41, v41
	v_cmp_lt_i32_e32 vcc, s50, v137
	s_and_b64 vcc, vcc, s[8:9]
	v_fma_f32 v41, -v163, v41, v45
	v_sub_f32_e32 v41, v41, v164
	v_exp_f32_e32 v41, v41
	s_nop 0
	v_cndmask_b32_e32 v41, 0, v41, vcc
	v_add_f32_e32 v40, v41, v40
	v_cvt_pk_bf16_f32 v39, v39, v41
	v_add_u32_e32 v41, 3, v165
	v_cmp_gt_u32_e64 s[8:9], s23, v41
	v_cvt_f32_i32_e32 v41, v41
	v_cmp_lt_i32_e32 vcc, s51, v137
	s_and_b64 vcc, vcc, s[8:9]
	v_cmp_gt_u32_e64 s[8:9], s23, v42
	v_cvt_f32_i32_e32 v42, v42
	v_fma_f32 v41, -v163, v41, v46
	v_sub_f32_e32 v41, v41, v164
	v_exp_f32_e32 v41, v41
	v_fma_f32 v42, -v163, v42, v47
	v_sub_f32_e32 v42, v42, v164
	v_exp_f32_e32 v42, v42
	v_cndmask_b32_e32 v41, 0, v41, vcc
	v_cmp_lt_i32_e32 vcc, s52, v137
	s_and_b64 vcc, vcc, s[8:9]
	v_add_f32_e32 v40, v41, v40
	v_cndmask_b32_e32 v42, 0, v42, vcc
	v_add_f32_e32 v46, v42, v40
	v_cvt_pk_bf16_f32 v40, v41, v42
	v_add_u32_e32 v41, 1, v165
	v_cmp_gt_u32_e64 s[8:9], s23, v41
	v_cvt_f32_i32_e32 v41, v41
	v_cmp_lt_i32_e32 vcc, s53, v137
	s_and_b64 vcc, vcc, s[8:9]
	v_cmp_gt_u32_e64 s[8:9], s23, v165
	v_fma_f32 v41, -v163, v41, v48
	v_sub_f32_e32 v41, v41, v164
	v_exp_f32_e32 v41, v41
	s_nop 0
	v_cndmask_b32_e32 v47, 0, v41, vcc
	v_cvt_f32_i32_e32 v41, v165
	v_cmp_lt_i32_e32 vcc, s56, v137
	s_and_b64 vcc, vcc, s[8:9]
	v_add_u32_e32 v137, 32, v137
	v_fma_f32 v41, -v163, v41, v49
	v_sub_f32_e32 v41, v41, v164
	v_exp_f32_e32 v41, v41
	v_subrev_u32_e32 v165, 32, v165
	s_cmp_lt_u32 s80, 4
	v_cndmask_b32_e32 v48, 0, v41, vcc
	v_cvt_pk_bf16_f32 v41, v47, v48
	ds_write_b128 v160, v[102:105]
	ds_write_b128 v160, v[106:109] offset:16
	ds_read_b64_tr_b16 v[42:43], v161
	ds_read_b64_tr_b16 v[44:45], v161 offset:256
	s_waitcnt lgkmcnt(0)
; #define LAS __attribute__((address_space(3)))
; __device__ __forceinline__ void attn_tile(const WT& w, float kbound, float mfloor, LAS unsigned char* stg, f32x16 (&O)[2], float& ltot, float& Mq) {
;     ...
; #pragma unroll
;         for (int t = 0; t < 2; ++t) {
;             LAS unsigned char* wp = stg + (lane & 2) * 512 + (lane >> 2) * 64 + (lane & 1) * 32;
;             *(LAS u32x4*)wp = vv[t][0]; *(LAS u32x4*)(wp + 16) = vv[t][1];
;             asm volatile("" ::: "memory");
; #pragma unroll
;             for (int dt = 0; dt < 2; ++dt) {
;                 const LAS unsigned char* rp = stg + dt * 1024 + (8 * g + ((lane & 15) >> 2)) * 64 + (16 * ((lane >> 4) & 1) + 4 * (lane & 3)) * 2;
;                 const s16x4 lo4 = __builtin_amdgcn_ds_read_tr16_b64_v4i16((LAS s16x4*)rp), hi4 = __builtin_amdgcn_ds_read_tr16_b64_v4i16((LAS s16x4*)(rp + 256));
;                 const bf16x8 va = {lo4[0], lo4[1], lo4[2], lo4[3], hi4[0], hi4[1], hi4[2], hi4[3]};
;                 O[dt] = __builtin_amdgcn_mfma_f32_32x32x16_bf16(va, pb[t], O[dt], 0, 0, 0);
;             }
;             asm volatile("" ::: "memory");
;         }
; #pragma unroll
;         for (int c = 0; c < 4; ++c) ka[c] = nk[c];
;         vv[0][0] = nv[0][0]; vv[0][1] = nv[0][1]; vv[1][0] = nv[1][0]; vv[1][1] = nv[1][1];
	v_mfma_f32_32x32x16_bf16 v[18:33], v[42:45], v[34:37], v[18:33]
	ds_read_b64_tr_b16 v[42:43], v161 offset:1024
	ds_read_b64_tr_b16 v[44:45], v161 offset:1280
	ds_write_b128 v160, v[110:113]
	ds_write_b128 v160, v[98:101] offset:16
	s_waitcnt vmcnt(0)
	v_mov_b64_e32 v[100:101], v[96:97]
	v_mov_b64_e32 v[98:99], v[94:95]
	v_mov_b32_e32 v102, v74
	s_waitcnt lgkmcnt(2)
	v_mfma_f32_32x32x16_bf16 v[2:17], v[42:45], v[34:37], v[2:17]
	ds_read_b64_tr_b16 v[34:35], v161
	ds_read_b64_tr_b16 v[36:37], v161 offset:256
	v_mov_b32_e32 v103, v75
	v_mov_b32_e32 v104, v76
	v_mov_b32_e32 v105, v77
	v_mov_b32_e32 v106, v70
	v_mov_b32_e32 v107, v71
	v_mov_b32_e32 v108, v72
	s_waitcnt lgkmcnt(0)
	v_mfma_f32_32x32x16_bf16 v[18:33], v[34:37], v[38:41], v[18:33]
	ds_read_b64_tr_b16 v[34:35], v161 offset:1024
	ds_read_b64_tr_b16 v[36:37], v161 offset:1280
	v_mov_b32_e32 v109, v73
	v_mov_b32_e32 v110, v66
	v_mov_b32_e32 v111, v67
	v_mov_b32_e32 v112, v68
	v_mov_b32_e32 v113, v69
	s_waitcnt lgkmcnt(0)
	v_mfma_f32_32x32x16_bf16 v[2:17], v[34:37], v[38:41], v[2:17]
	v_add_f32_e32 v34, v47, v46
	v_add_f32_e32 v166, v48, v34
	s_mov_b32 vcc_lo, 0xaaaaaaaa
	s_mov_b32 vcc_hi, 0xaaaaaaaa
	v_cndmask_b32_dpp v188, v78, v82, vcc quad_perm:[1,0,3,2] row_mask:0xf bank_mask:0xf
	v_cndmask_b32_dpp v189, v79, v83, vcc quad_perm:[1,0,3,2] row_mask:0xf bank_mask:0xf
	v_cndmask_b32_dpp v190, v80, v84, vcc quad_perm:[1,0,3,2] row_mask:0xf bank_mask:0xf
	v_cndmask_b32_dpp v191, v81, v85, vcc quad_perm:[1,0,3,2] row_mask:0xf bank_mask:0xf
	v_cndmask_b32_dpp v196, v86, v90, vcc quad_perm:[1,0,3,2] row_mask:0xf bank_mask:0xf
	v_cndmask_b32_dpp v197, v87, v91, vcc quad_perm:[1,0,3,2] row_mask:0xf bank_mask:0xf
	v_cndmask_b32_dpp v198, v88, v92, vcc quad_perm:[1,0,3,2] row_mask:0xf bank_mask:0xf
	v_cndmask_b32_dpp v199, v89, v93, vcc quad_perm:[1,0,3,2] row_mask:0xf bank_mask:0xf
	s_mov_b32 vcc_lo, 0x55555555
	s_mov_b32 vcc_hi, 0x55555555
	v_cndmask_b32_dpp v184, v82, v78, vcc quad_perm:[1,0,3,2] row_mask:0xf bank_mask:0xf
	v_cndmask_b32_dpp v185, v83, v79, vcc quad_perm:[1,0,3,2] row_mask:0xf bank_mask:0xf
	v_cndmask_b32_dpp v186, v84, v80, vcc quad_perm:[1,0,3,2] row_mask:0xf bank_mask:0xf
	v_cndmask_b32_dpp v187, v85, v81, vcc quad_perm:[1,0,3,2] row_mask:0xf bank_mask:0xf
	v_cndmask_b32_dpp v192, v90, v86, vcc quad_perm:[1,0,3,2] row_mask:0xf bank_mask:0xf
	v_cndmask_b32_dpp v193, v91, v87, vcc quad_perm:[1,0,3,2] row_mask:0xf bank_mask:0xf
	v_cndmask_b32_dpp v194, v92, v88, vcc quad_perm:[1,0,3,2] row_mask:0xf bank_mask:0xf
	v_cndmask_b32_dpp v195, v93, v89, vcc quad_perm:[1,0,3,2] row_mask:0xf bank_mask:0xf
	s_mov_b32 vcc_lo, 0xcccccccc
	s_mov_b32 vcc_hi, 0xcccccccc
	s_nop 1
	v_cndmask_b32_dpp v118, v184, v192, vcc quad_perm:[2,3,0,1] row_mask:0xf bank_mask:0xf
	v_cndmask_b32_dpp v119, v185, v193, vcc quad_perm:[2,3,0,1] row_mask:0xf bank_mask:0xf
	v_cndmask_b32_dpp v120, v186, v194, vcc quad_perm:[2,3,0,1] row_mask:0xf bank_mask:0xf
	v_cndmask_b32_dpp v121, v187, v195, vcc quad_perm:[2,3,0,1] row_mask:0xf bank_mask:0xf
	v_cndmask_b32_dpp v114, v188, v196, vcc quad_perm:[2,3,0,1] row_mask:0xf bank_mask:0xf
	v_cndmask_b32_dpp v115, v189, v197, vcc quad_perm:[2,3,0,1] row_mask:0xf bank_mask:0xf
	v_cndmask_b32_dpp v116, v190, v198, vcc quad_perm:[2,3,0,1] row_mask:0xf bank_mask:0xf
	v_cndmask_b32_dpp v117, v191, v199, vcc quad_perm:[2,3,0,1] row_mask:0xf bank_mask:0xf
	s_mov_b32 vcc_lo, 0x33333333
	s_mov_b32 vcc_hi, 0x33333333
	v_cndmask_b32_dpp v34, v192, v184, vcc quad_perm:[2,3,0,1] row_mask:0xf bank_mask:0xf
	v_cndmask_b32_dpp v35, v193, v185, vcc quad_perm:[2,3,0,1] row_mask:0xf bank_mask:0xf
	v_cndmask_b32_dpp v36, v194, v186, vcc quad_perm:[2,3,0,1] row_mask:0xf bank_mask:0xf
	v_cndmask_b32_dpp v37, v195, v187, vcc quad_perm:[2,3,0,1] row_mask:0xf bank_mask:0xf
	v_cndmask_b32_dpp v122, v196, v188, vcc quad_perm:[2,3,0,1] row_mask:0xf bank_mask:0xf
	v_cndmask_b32_dpp v123, v197, v189, vcc quad_perm:[2,3,0,1] row_mask:0xf bank_mask:0xf
	v_cndmask_b32_dpp v124, v198, v190, vcc quad_perm:[2,3,0,1] row_mask:0xf bank_mask:0xf
	v_cndmask_b32_dpp v125, v199, v191, vcc quad_perm:[2,3,0,1] row_mask:0xf bank_mask:0xf
	s_cbranch_scc1 .LBB0_652
